# G1 phase: odd workgroups start 8128 clocks later so the two halves' epilogue store bursts do not collide in HBM
# baseline (speedup 1.0000x reference)
;     __device__ bool next(int i, Unit& u) const {
;         const long L = (long)lo + (long)i * G + c; if (L >= hi) return false; u.L = (int)L;
;         int wgid = (int)L; { const int q = nwg / NXCD, r = nwg % NXCD, xcd = wgid % NXCD, off = wgid / NXCD; wgid = (xcd < r ? xcd * (q + 1) : r * (q + 1) + (xcd - r) * q) + off; }
;         const int nig = WGM * nN, gid = wgid / nig, fm = gid * WGM, gsz = (nM - fm) < WGM ? (nM - fm) : WGM;
;         u.pm = fm + ((wgid % nig) % gsz); u.pn = (wgid % nig) / gsz; return true;
; template <class Epi>
; __device__ __forceinline__ void gemm_phase(LAS unsigned char* lds, const Gemm g, const StaticOrder& S, const Epi& E) {
;     ...
;     Unit cur, nxt; int ui = 0;
;     if (!S.next(0, cur)) return;
.LBB0_588:
	s_andn2_b64 vcc, exec, s[2:3]
	s_cbranch_vccnz .LBB0_716
	s_bitcmp1_b32 s77, 0
	s_cbranch_scc0 .Lg1_nostag
	s_sleep 127
.Lg1_nostag:
	v_mov_b32_e32 v0, v162
	s_cmpk_lt_i32 s77, 0x800
	s_movk_i32 s6, 0x400
	v_readfirstlane_b32 s10, v0
	s_cselect_b64 s[2:3], -1, 0
	s_cmpk_gt_i32 s77, 0x7ff
	s_cbranch_scc1 .LBB0_595
	s_ashr_i32 s0, s77, 31
	s_lshr_b32 s0, s0, 29
	s_add_i32 s0, s77, s0
	s_and_b32 s4, s0, -8
	s_sub_i32 s7, s77, s4
	s_cmp_gt_i32 s7, -1
	s_mov_b64 s[4:5], -1
	s_cbranch_scc0 .LBB0_592
	s_lshl_b32 s8, s7, 8
	s_mov_b64 s[4:5], 0
